# SEAM 6/7/8 grid barriers -> 16-workgroup group barriers (GEMM chain P6..P9 is closed within blockIdx&15 groups on one XCD); no fallback check yet
# speedup vs baseline: 1.0195x; 1.0195x over previous
.LBB0_629:
	s_cmp_gt_i32 s95, 7
	s_cselect_b64 s[0:1], -1, 0
	s_and_b64 s[4:5], s[4:5], s[0:1]
	s_andn2_b64 vcc, exec, s[4:5]
	s_cbranch_vccnz .LBB0_683
	s_waitcnt vmcnt(0)
	s_waitcnt vmcnt(0)
	s_barrier
	s_mov_b64 s[4:5], exec
	v_readlane_b32 s6, v246, 2
	v_readlane_b32 s7, v246, 3
	s_and_b64 s[6:7], s[4:5], s[6:7]
	s_mov_b64 exec, s[6:7]
	s_cbranch_execz .LBB0_682
	s_and_b32 s6, s2, 15
	s_lshl_b32 s6, s6, 8
	s_add_u32 s6, s92, s6
	s_addc_u32 s7, s93, 0
	s_add_u32 s6, s6, 0x53000
	s_addc_u32 s7, s7, 0
	s_add_u32 s8, s92, 0x54000
	s_addc_u32 s9, s93, 0
	v_mov_b32_e32 v1, 0
	v_mov_b32_e32 v2, 1
	global_atomic_add v1, v2, s[6:7]
	global_atomic_add v1, v2, s[8:9]
	s_mov_b32 s10, 0x400000
	s_movk_i32 s11, 15
.Lgb6_poll:
	global_load_dword v3, v1, s[6:7] sc1
	s_waitcnt vmcnt(0)
	v_cmp_lt_u32_e32 vcc, s11, v3
	s_cbranch_vccnz .Lgb6_ok
	s_sleep 1
	s_sub_u32 s10, s10, 1
	s_cmp_lg_u32 s10, 0
	s_cbranch_scc1 .Lgb6_poll
.Lgb6_ok:
	buffer_inv sc1
	s_waitcnt vmcnt(0)
	s_branch .LBB0_682
	s_add_i32 s6, 0, 0x22000
	v_mov_b32_e32 v1, s6
	s_waitcnt vmcnt(0) expcnt(0) lgkmcnt(0)
	ds_read_b32 v3, v1
	s_add_i32 s6, 0, 0x22004
	v_mov_b32_e32 v1, s6
	ds_read_b32 v1, v1
	s_waitcnt lgkmcnt(1)
	v_cmp_ne_u32_e32 vcc, 0, v3
	s_cbranch_vccnz .LBB0_646
	v_readlane_b32 s6, v246, 0
	v_readlane_b32 s7, v246, 1
	s_load_dwordx2 s[10:11], s[6:7], 0x4
	s_add_u32 s6, s92, 0x1000
	s_addc_u32 s7, s93, 0
	s_add_u32 s8, s92, 0x1100
	s_addc_u32 s9, s93, 0
	s_waitcnt lgkmcnt(0)
	s_mul_i32 s20, s10, s3
	s_add_u32 s10, s92, 0x1200
	s_mul_i32 s20, s20, s11
	s_addc_u32 s11, s93, 0
	s_add_u32 s12, s92, 0x1300
	s_addc_u32 s13, s93, 0
	s_mov_b32 s21, 1
	v_mov_b32_e32 v17, 0
	s_branch .LBB0_634

.LBB0_761:
	s_cmp_gt_i32 s95, 8
	s_cselect_b64 s[0:1], -1, 0
	s_and_b64 s[4:5], s[6:7], s[0:1]
	s_andn2_b64 vcc, exec, s[4:5]
	s_cbranch_vccnz .LBB0_815
	s_waitcnt vmcnt(0)
	s_waitcnt vmcnt(0)
	s_barrier
	s_mov_b64 s[4:5], exec
	v_readlane_b32 s6, v246, 2
	v_readlane_b32 s7, v246, 3
	s_and_b64 s[6:7], s[4:5], s[6:7]
	s_mov_b64 exec, s[6:7]
	s_cbranch_execz .LBB0_814
	s_and_b32 s6, s2, 15
	s_lshl_b32 s6, s6, 8
	s_add_u32 s6, s92, s6
	s_addc_u32 s7, s93, 0
	s_add_u32 s6, s6, 0x53000
	s_addc_u32 s7, s7, 0
	s_add_u32 s8, s92, 0x54000
	s_addc_u32 s9, s93, 0
	v_mov_b32_e32 v1, 0
	v_mov_b32_e32 v2, 1
	global_atomic_add v1, v2, s[6:7]
	s_mov_b32 s10, 0x400000
	s_movk_i32 s11, 31

.Lgb7_ok:
	s_movk_i32 s11, 0xff
.Lgb7_poll2:
	global_load_dword v3, v1, s[8:9] sc1
	s_waitcnt vmcnt(0)
	v_cmp_lt_u32_e32 vcc, s11, v3
	s_cbranch_vccnz .Lgb7_ok2
	s_sleep 1
	s_sub_u32 s10, s10, 1
	s_cmp_lg_u32 s10, 0
	s_cbranch_scc1 .Lgb7_poll2

.LBB0_836:
	s_cmp_gt_i32 s95, 9
	s_cselect_b64 s[0:1], -1, 0
	s_and_b64 s[4:5], s[4:5], s[0:1]
	s_andn2_b64 vcc, exec, s[4:5]
	s_cbranch_vccnz .LBB0_890
	s_waitcnt vmcnt(0)
	s_waitcnt vmcnt(0)
	s_barrier
	s_mov_b64 s[4:5], exec
	v_readlane_b32 s6, v246, 2
	v_readlane_b32 s7, v246, 3
	s_and_b64 s[6:7], s[4:5], s[6:7]
	s_mov_b64 exec, s[6:7]
	s_cbranch_execz .LBB0_889
	s_and_b32 s6, s2, 15
	s_lshl_b32 s6, s6, 8
	s_add_u32 s6, s92, s6
	s_addc_u32 s7, s93, 0
	s_add_u32 s6, s6, 0x53000
	s_addc_u32 s7, s7, 0
	s_add_u32 s8, s92, 0x54000
	s_addc_u32 s9, s93, 0
	v_mov_b32_e32 v1, 0
	v_mov_b32_e32 v2, 1
	global_atomic_add v1, v2, s[6:7]
	s_mov_b32 s10, 0x400000
	s_movk_i32 s11, 47
